# MIX order selector bit4 instead of bit3
# baseline (speedup 1.0000x reference)
; #define GEMMCALL if (0)
; #define FRESH_TID() asm volatile("" : "+v"(tid))
; __global__ void __launch_bounds__(NTHREADS, 2) mega(Params p) {
;     ...
;             for (int rep = 0; rep < REP_FOUR; ++rep) { FRESH_TID(); fft_phase(p, lds, tid); }
;             if (l == 0) {
;                 pg8::Gemm g{(const bf16_t*)(ws + WS_CTC), (const bf16_t*)(ws + WS_ZTC), 256, 2048, 512}; pg8::StaticOrder S; S.init(256, 2048, G, (int)blockIdx.x);
;                 EpiStore<0> E{MIX + (size_t)MX * KOUT + 512, KOUT, (size_t)256 * KOUT};
;                 GEMMCALL pg8::gemm_phase<EpiStore<0>, pg8::StaticOrder, true, true>(lds, g, S, E);
;             }
;             __syncthreads();
;             for (int rep = 0; rep < REP_ATTN; ++rep) { FRESH_TID(); attn_phase(p, l, lds, tid); }
.LBB0_452:
	s_or_b64 exec, exec, s[0:1]
	v_readlane_b32 s0, v254, 56
	v_readlane_b32 s1, v254, 57
	s_andn2_b64 vcc, exec, s[0:1]
	s_waitcnt lgkmcnt(0)
	s_barrier
	s_mov_b32 s68, 0
	s_bitcmp1_b32 s2, 4
	s_cbranch_scc0 .Lmix_norm
	s_mov_b32 s68, 1
	s_branch .LBB0_455
